# CONV7: conv tile staged in LDS as raw bf16 rows (half the LDS store traffic, 24 fewer unpack VALU at the write side), taps widened after the read; on top of DPP+CONV5+CONV6
# speedup vs baseline: 1.0040x; 1.0040x over previous
; #define LAS __attribute__((address_space(3)))
; __device__ __forceinline__ float bflo(unsigned w) { return __uint_as_float(w << 16); }
; __device__ __forceinline__ float bfhi(unsigned w) { return __uint_as_float(w & 0xffff0000u); }
; __device__ __forceinline__ void phase_conv(const Params& p, LAS unsigned char* lds, int wg, int G, int tid) {
;     ...
;         LAS float* tile = (LAS float*)(lds + buf * 34816);
; #pragma unroll
;         for (int i = 0; i < 3; ++i) { const int idx = tid + 512 * i;
;             if (idx < 134 * 8) { LAS float* d = tile + (idx >> 3) * 64 + (idx & 7) * 8; const u32x4 w = rg[i];
;                 *(LAS f32x4*)d = (f32x4){bflo(w.x), bfhi(w.x), bflo(w.y), bfhi(w.y)}; *(LAS f32x4*)(d + 4) = (f32x4){bflo(w.z), bfhi(w.z), bflo(w.w), bfhi(w.w)}; } }
.LBB0_628:
	s_mul_i32 s20, s33, 0x8800
	s_add_i32 s44, s20, 0
	v_lshl_add_u32 v12, v50, 1, s44
	s_and_saveexec_b64 s[20:21], s[2:3]
	s_cbranch_execnz .LBB0_671
	s_or_b64 exec, exec, s[20:21]
	s_and_saveexec_b64 s[20:21], s[8:9]
	s_cbranch_execnz .LBB0_672

; #define LAS __attribute__((address_space(3)))
; __device__ __forceinline__ float bflo(unsigned w) { return __uint_as_float(w << 16); }
; __device__ __forceinline__ float bfhi(unsigned w) { return __uint_as_float(w & 0xffff0000u); }
; __device__ __forceinline__ void phase_conv(const Params& p, LAS unsigned char* lds, int wg, int G, int tid) {
;     ...
;         for (int i = 0; i < 3; ++i) { const int idx = tid + 512 * i;
;             if (idx < 134 * 8) { LAS float* d = tile + (idx >> 3) * 64 + (idx & 7) * 8; const u32x4 w = rg[i];
;                 *(LAS f32x4*)d = (f32x4){bflo(w.x), bfhi(w.x), bflo(w.y), bfhi(w.y)}; *(LAS f32x4*)(d + 4) = (f32x4){bflo(w.z), bfhi(w.z), bflo(w.w), bfhi(w.w)}; } }
.LBB0_631:
	v_lshl_add_u32 v16, v62, 1, v12
	ds_write_b128 v16, v[8:11]

; #define LAS __attribute__((address_space(3)))
; __device__ __forceinline__ void conv_fetch(const bf16_t* raw, int item, int tid, u32x4 (&rg)[3]) {
;     constexpr int NFB = 80;
;     const int ch = item / NFB, fb = item % NFB;
;     const bool is_ctx = ch < (CGR / 128);
;     const long row0 = (long)ch * 128;
; #pragma unroll
;     for (int i = 0; i < 3; ++i) {
;         const int idx = tid + 512 * i;
;         rg[i] = (u32x4){0u, 0u, 0u, 0u};
;         if (idx < 134 * 8) { const int ir = idx >> 3, c8 = idx & 7; int tok; bool ok;
;             if (is_ctx) { tok = ir - 2; const int gt = (ch & 1) * 128 + tok; ok = (ir < 131) && gt >= 0 && gt < 256; }
;             else { const int sg = ir >= 67 ? 1 : 0, q = ir - 67 * sg; tok = 64 * sg + q - 2; ok = q >= 2 && q < 66; }
;             if (ok) rg[i] = *(const u32x4*)(raw + (size_t)(row0 + tok) * NA + fb * 64 + c8 * 8); }
; __device__ __forceinline__ void phase_conv(const Params& p, LAS unsigned char* lds, int wg, int G, int tid) {
;     ...
;         const int ch = item / NFB, fb = item % NFB;
;         const size_t row0 = (size_t)ch * 128;
;         const int fp = tid & 31, tq = tid >> 5;
;         const int feat = fb * 64 + 2 * fp;
;         f32x2 w0, w1, w2, w3, bias;
;         if (feat < 4096) { w0 = *(const f32x2*)(p.ssd_conv_w + feat); w1 = *(const f32x2*)(p.ssd_conv_w + 4096 + feat); w2 = *(const f32x2*)(p.ssd_conv_w + 8192 + feat); w3 = *(const f32x2*)(p.ssd_conv_w + 12288 + feat); bias = *(const f32x2*)(p.ssd_conv_b + feat); }
;         else { const int lf = feat - 4096; w0 = *(const f32x2*)(p.lru_conv_w + lf); w1 = *(const f32x2*)(p.lru_conv_w + 1024 + lf); w2 = *(const f32x2*)(p.lru_conv_w + 2048 + lf); w3 = *(const f32x2*)(p.lru_conv_w + 3072 + lf); bias = *(const f32x2*)(p.lru_conv_b + lf); }
;         const bool is_ctx = ch < (CGR / 128);
;         const bool act = fb < 64;
;         f32x2 o[8];
;         const int ib0 = is_ctx ? tq * 8 : (tq >> 3) * 67 + (tq & 7) * 8;
;         const LAS f32x2* tp = (const LAS f32x2*)tile + fp;
;         f32x2 v0 = tp[(ib0 + 0) * 32], v1 = tp[(ib0 + 1) * 32], v2 = tp[(ib0 + 2) * 32];
; #pragma unroll
;         for (int k = 0; k < 8; ++k) {
;             const f32x2 v3 = tp[(ib0 + k + 3) * 32];
;             f32x2 a = bias + w0 * v0 + w1 * v1 + w2 * v2 + w3 * v3;
.LBB0_650:
	s_or_b64 exec, exec, s[20:21]
	global_load_dwordx2 v[30:31], v[12:13], off
	global_load_dwordx2 v[32:33], v[28:29], off
	global_load_dwordx2 v[38:39], v[14:15], off
	global_load_dwordx2 v[36:37], v[16:17], off
	global_load_dwordx2 v[34:35], v[18:19], off
	s_mul_i32 s20, s48, 0xffffffb0
	s_add_i32 s45, s41, s20
	s_cmpk_lt_i32 s41, 0xa00
	s_cselect_b64 s[20:21], -1, 0
	v_cndmask_b32_e64 v12, v59, v22, s[20:21]
	v_lshl_add_u32 v13, v57, 2, s44
	v_lshlrev_b32_e32 v12, 7, v12
	v_add_u32_e32 v27, v13, v12
	ds_read2_b32 v[86:87], v27 offset1:32
	ds_read2_b32 v[88:89], v27 offset0:64 offset1:96
	s_cmp_lt_i32 s45, 64
	s_cselect_b64 s[50:51], -1, 0
	s_cmp_gt_i32 s45, 63
	s_waitcnt vmcnt(3) lgkmcnt(1)
	v_lshlrev_b32_e32 v16, 16, v86
	v_and_b32_e32 v17, 0xffff0000, v86
	v_lshlrev_b32_e32 v18, 16, v87
	v_and_b32_e32 v19, 0xffff0000, v87
	v_pk_fma_f32 v[16:17], v[30:31], v[16:17], v[32:33]
	s_waitcnt vmcnt(2)
	v_pk_fma_f32 v[16:17], v[38:39], v[18:19], v[16:17]
	s_waitcnt vmcnt(1) lgkmcnt(0)
	v_lshlrev_b32_e32 v12, 16, v88
	v_and_b32_e32 v13, 0xffff0000, v88
	v_lshlrev_b32_e32 v14, 16, v89
	v_and_b32_e32 v15, 0xffff0000, v89
	v_pk_fma_f32 v[16:17], v[36:37], v[12:13], v[16:17]
	s_waitcnt vmcnt(0)
	v_pk_fma_f32 v[16:17], v[34:35], v[14:15], v[16:17]
	v_mov_b32_e32 v0, v68
	v_mov_b32_e32 v1, v69
	v_mov_b32_e32 v2, v70
	v_mov_b32_e32 v3, v71
	v_mov_b32_e32 v4, v72
	v_mov_b32_e32 v5, v73
	v_mov_b32_e32 v6, v74
	v_mov_b32_e32 v7, v75
	v_mov_b32_e32 v8, v76
	v_mov_b32_e32 v9, v77
	v_mov_b32_e32 v10, v78
	v_mov_b32_e32 v11, v79
	s_mov_b32 s101, s45
	v_writelane_b32 v255, s48, 63
	v_writelane_b32 v255, s50, 59
	v_writelane_b32 v255, s51, 60
	s_add_i32 s100, s40, s34
	s_cmpk_gt_i32 s100, 0x59ff
	s_cbranch_scc1 .Lconv_nopf
	s_mul_hi_i32 s20, s100, 0x66666667
	s_lshr_b32 s21, s20, 31
	s_ashr_i32 s20, s20, 5
	s_add_i32 s20, s20, s21
	s_cmpk_lt_i32 s100, 0xa00
	s_cselect_b64 vcc, -1, 0
	s_ashr_i32 s21, s20, 31
	s_lshl_b64 s[22:23], s[20:21], 7
	s_lshl_b32 s21, s20, 7
	s_and_b32 s45, s21, 0x80
	s_mulk_i32 s20, 0xec00
	s_add_i32 s21, s39, s38
	s_add_i32 s21, s21, s39
	s_add_i32 s20, s21, s20
	s_ashr_i32 s21, s20, 31
	v_lshl_add_u64 v[66:67], s[20:21], 1, v[20:21]
	s_cbranch_vccnz .Lconv_l_ctx
	s_mul_hi_u32 s49, s22, s78
	s_mul_i32 s48, s22, s78
	v_mov_b32_e32 v68, 0
	v_mov_b32_e32 v69, 0
	v_mov_b32_e32 v70, 0
	v_mov_b32_e32 v71, 0
	v_mov_b32_e32 v72, 0
	v_mov_b32_e32 v73, 0
	v_mov_b32_e32 v74, 0
	v_mov_b32_e32 v75, 0
	v_mov_b32_e32 v76, 0
	v_mov_b32_e32 v77, 0
	v_mov_b32_e32 v78, 0
	v_mov_b32_e32 v79, 0
	v_lshl_add_u64 v[66:67], v[66:67], 0, s[48:49]
	s_and_b64 s[20:21], s[2:3], s[4:5]
	s_and_saveexec_b64 s[50:51], s[20:21]
	v_lshl_add_u64 v[70:71], v[80:81], 0, v[66:67]
	global_load_dwordx4 v[68:71], v[70:71], off
	s_or_b64 exec, exec, s[50:51]
	s_and_b64 s[20:21], s[8:9], s[10:11]
	s_and_saveexec_b64 s[50:51], s[20:21]
	v_lshl_add_u64 v[74:75], v[82:83], 0, v[66:67]
	global_load_dwordx4 v[72:75], v[74:75], off
	s_or_b64 exec, exec, s[50:51]
	s_and_b64 s[20:21], s[14:15], s[16:17]
	s_and_saveexec_b64 s[50:51], s[20:21]
	v_lshl_add_u64 v[78:79], v[84:85], 0, v[66:67]
	global_load_dwordx4 v[76:79], v[78:79], off
	s_or_b64 exec, exec, s[50:51]
	s_branch .Lconv_l_done

; __device__ __forceinline__ void phase_conv(const Params& p, LAS unsigned char* lds, int wg, int G, int tid) {
;     ...
;         f32x2 v0 = tp[(ib0 + 0) * 32], v1 = tp[(ib0 + 1) * 32], v2 = tp[(ib0 + 2) * 32];
; #pragma unroll
;         for (int k = 0; k < 8; ++k) {
;             const f32x2 v3 = tp[(ib0 + k + 3) * 32];
;             f32x2 a = bias + w0 * v0 + w1 * v1 + w2 * v2 + w3 * v3;
;             if (act) { f32x2 d; d.x = 1.f + __expf(-a.x); d.y = 1.f + __expf(-a.y); f32x2 rc; rc.x = __builtin_amdgcn_rcpf(d.x); rc.y = __builtin_amdgcn_rcpf(d.y); a = a * rc; }
;             o[k] = a;
;             v0 = v1; v1 = v2; v2 = v3;
;         }
.LBB0_652:
	ds_read_b32 v90, v27 offset:512
	ds_read_b32 v91, v27 offset:640
	ds_read_b32 v92, v27 offset:768
	ds_read_b32 v93, v27 offset:896
	ds_read_b32 v94, v27 offset:1024
	ds_read_b32 v95, v27 offset:1152
	ds_read_b32 v96, v27 offset:1280
	v_pk_fma_f32 v[100:101], v[30:31], v[18:19], v[32:33]
	v_pk_fma_f32 v[102:103], v[30:31], v[12:13], v[32:33]
	v_pk_fma_f32 v[104:105], v[30:31], v[14:15], v[32:33]
	s_waitcnt lgkmcnt(0)
	v_lshlrev_b32_e32 v28, 16, v90
	v_and_b32_e32 v29, 0xffff0000, v90
	v_lshlrev_b32_e32 v40, 16, v91
	v_and_b32_e32 v41, 0xffff0000, v91
	v_lshlrev_b32_e32 v42, 16, v92
	v_and_b32_e32 v43, 0xffff0000, v92
	v_lshlrev_b32_e32 v44, 16, v93
	v_and_b32_e32 v45, 0xffff0000, v93
	v_lshlrev_b32_e32 v46, 16, v94
	v_and_b32_e32 v47, 0xffff0000, v94
	v_lshlrev_b32_e32 v48, 16, v95
	v_and_b32_e32 v49, 0xffff0000, v95
	v_lshlrev_b32_e32 v64, 16, v96
	v_and_b32_e32 v65, 0xffff0000, v96
	v_pk_fma_f32 v[106:107], v[30:31], v[28:29], v[32:33]
	v_pk_fma_f32 v[108:109], v[30:31], v[40:41], v[32:33]
	v_pk_fma_f32 v[110:111], v[30:31], v[42:43], v[32:33]
	v_pk_fma_f32 v[112:113], v[30:31], v[44:45], v[32:33]
	v_pk_fma_f32 v[100:101], v[38:39], v[12:13], v[100:101]
	v_pk_fma_f32 v[102:103], v[38:39], v[14:15], v[102:103]
	v_pk_fma_f32 v[104:105], v[38:39], v[28:29], v[104:105]
	v_pk_fma_f32 v[106:107], v[38:39], v[40:41], v[106:107]
	v_pk_fma_f32 v[108:109], v[38:39], v[42:43], v[108:109]
	v_pk_fma_f32 v[110:111], v[38:39], v[44:45], v[110:111]
	v_pk_fma_f32 v[112:113], v[38:39], v[46:47], v[112:113]
	v_pk_fma_f32 v[100:101], v[36:37], v[14:15], v[100:101]
	v_pk_fma_f32 v[102:103], v[36:37], v[28:29], v[102:103]
	v_pk_fma_f32 v[104:105], v[36:37], v[40:41], v[104:105]
	v_pk_fma_f32 v[106:107], v[36:37], v[42:43], v[106:107]
	v_pk_fma_f32 v[108:109], v[36:37], v[44:45], v[108:109]
	v_pk_fma_f32 v[110:111], v[36:37], v[46:47], v[110:111]
	v_pk_fma_f32 v[112:113], v[36:37], v[48:49], v[112:113]
	v_pk_fma_f32 v[100:101], v[34:35], v[28:29], v[100:101]
	v_pk_fma_f32 v[102:103], v[34:35], v[40:41], v[102:103]
	v_pk_fma_f32 v[104:105], v[34:35], v[42:43], v[104:105]
	v_pk_fma_f32 v[106:107], v[34:35], v[44:45], v[106:107]
	v_pk_fma_f32 v[108:109], v[34:35], v[46:47], v[108:109]
	v_pk_fma_f32 v[110:111], v[34:35], v[48:49], v[110:111]
	v_pk_fma_f32 v[112:113], v[34:35], v[64:65], v[112:113]
	s_andn2_b64 vcc, exec, s[50:51]
	s_cbranch_vccnz .Lconv_nosilu
	v_mul_f32_e32 v114, 0xbfb8aa3b, v100
	v_mul_f32_e32 v115, 0xbfb8aa3b, v101
	v_mul_f32_e32 v116, 0xbfb8aa3b, v102
	v_mul_f32_e32 v117, 0xbfb8aa3b, v103
	v_mul_f32_e32 v118, 0xbfb8aa3b, v104
	v_mul_f32_e32 v119, 0xbfb8aa3b, v105
	v_mul_f32_e32 v120, 0xbfb8aa3b, v106
	v_mul_f32_e32 v121, 0xbfb8aa3b, v107
	v_mul_f32_e32 v122, 0xbfb8aa3b, v108
	v_mul_f32_e32 v123, 0xbfb8aa3b, v109
	v_mul_f32_e32 v124, 0xbfb8aa3b, v110
	v_mul_f32_e32 v125, 0xbfb8aa3b, v111
	v_mul_f32_e32 v126, 0xbfb8aa3b, v112
	v_mul_f32_e32 v127, 0xbfb8aa3b, v113
	v_exp_f32_e32 v114, v114
	v_exp_f32_e32 v115, v115
	v_exp_f32_e32 v116, v116
	v_exp_f32_e32 v117, v117
	v_exp_f32_e32 v118, v118
	v_exp_f32_e32 v119, v119
	v_exp_f32_e32 v120, v120
	v_exp_f32_e32 v121, v121
	v_exp_f32_e32 v122, v122
	v_exp_f32_e32 v123, v123
	v_exp_f32_e32 v124, v124
	v_exp_f32_e32 v125, v125
	v_exp_f32_e32 v126, v126
	v_exp_f32_e32 v127, v127
	v_add_f32_e32 v114, 1.0, v114
	v_add_f32_e32 v115, 1.0, v115
	v_add_f32_e32 v116, 1.0, v116
	v_add_f32_e32 v117, 1.0, v117
	v_add_f32_e32 v118, 1.0, v118
	v_add_f32_e32 v119, 1.0, v119
	v_add_f32_e32 v120, 1.0, v120
	v_add_f32_e32 v121, 1.0, v121
	v_add_f32_e32 v122, 1.0, v122
	v_add_f32_e32 v123, 1.0, v123
	v_add_f32_e32 v124, 1.0, v124
	v_add_f32_e32 v125, 1.0, v125
	v_add_f32_e32 v126, 1.0, v126
	v_add_f32_e32 v127, 1.0, v127
	v_rcp_f32_e32 v114, v114
	v_rcp_f32_e32 v115, v115
	v_rcp_f32_e32 v116, v116
	v_rcp_f32_e32 v117, v117
	v_rcp_f32_e32 v118, v118
	v_rcp_f32_e32 v119, v119
	v_rcp_f32_e32 v120, v120
	v_rcp_f32_e32 v121, v121
	v_rcp_f32_e32 v122, v122
	v_rcp_f32_e32 v123, v123
	v_rcp_f32_e32 v124, v124
	v_rcp_f32_e32 v125, v125
	v_rcp_f32_e32 v126, v126
	v_rcp_f32_e32 v127, v127
	s_nop 0
	v_pk_mul_f32 v[100:101], v[100:101], v[114:115]
	v_pk_mul_f32 v[102:103], v[102:103], v[116:117]
	v_pk_mul_f32 v[104:105], v[104:105], v[118:119]
	v_pk_mul_f32 v[106:107], v[106:107], v[120:121]
	v_pk_mul_f32 v[108:109], v[108:109], v[122:123]
	v_pk_mul_f32 v[110:111], v[110:111], v[124:125]
	v_pk_mul_f32 v[112:113], v[112:113], v[126:127]

; #define LAS __attribute__((address_space(3)))
; __device__ __forceinline__ float bflo(unsigned w) { return __uint_as_float(w << 16); }
; __device__ __forceinline__ float bfhi(unsigned w) { return __uint_as_float(w & 0xffff0000u); }
; __device__ __forceinline__ void phase_conv(const Params& p, LAS unsigned char* lds, int wg, int G, int tid) {
;     ...
; #pragma unroll
;         for (int i = 0; i < 3; ++i) { const int idx = tid + 512 * i;
;             if (idx < 134 * 8) { LAS float* d = tile + (idx >> 3) * 64 + (idx & 7) * 8; const u32x4 w = rg[i];
;                 *(LAS f32x4*)d = (f32x4){bflo(w.x), bfhi(w.x), bflo(w.y), bfhi(w.y)}; *(LAS f32x4*)(d + 4) = (f32x4){bflo(w.z), bfhi(w.z), bflo(w.w), bfhi(w.w)}; } }
.LBB0_671:
	v_lshl_add_u32 v13, v60, 1, v12
	ds_write_b128 v13, v[0:3]
	s_or_b64 exec, exec, s[20:21]
	s_and_saveexec_b64 s[20:21], s[8:9]
	s_cbranch_execz .LBB0_630
.LBB0_672:
	v_lshl_add_u32 v13, v61, 1, v12
	ds_write_b128 v13, v[4:7]
	s_or_b64 exec, exec, s[20:21]
	s_and_saveexec_b64 s[20:21], s[14:15]
	s_cbranch_execnz .LBB0_631
	s_branch .LBB0_632
